# NT2: nt hint on the 80 fp16-copy (XH) stores of the streaming waves in prologue phases 0 and 1 (code size unchanged)
# speedup vs baseline: 1.0087x; 1.0087x over previous
; __device__ void p0_xconv(const Args& a) {
;     ...
;         for (int r = 0; r < 4; ++r) {
;             const int row = row0 + r * nwv;
;             if (row < MROWS) {
;                 float ss = 0.f;
; #pragma unroll
;                 for (int i = 0; i < 4; ++i) {
;                     const f32x4 x = v[r][i];
;                     ss += (x[0] * x[0] + x[1] * x[1]) + (x[2] * x[2] + x[3] * x[3]);
;                     f16x4 h; h[0] = (f16)x[0]; h[1] = (f16)x[1]; h[2] = (f16)x[2]; h[3] = (f16)x[3];
;                     *(f16x4*)(XH + (size_t)row * DM + i * 256 + lane * 4) = h;
;                 }
; #pragma unroll
;                 for (int o = 1; o < 64; o <<= 1) ss += __shfl_xor(ss, o);
;                 if (lane < 16) SS[(size_t)row * 16 + lane] = (lane == 0) ? ss : 0.f;
;             }
.Lxc_100:
	s_or_b64 exec, exec, s[34:35]
	s_waitcnt vmcnt(0)
	v_mul_f32_e32 v73, v63, v63
	v_mul_f32_e32 v75, v65, v65
	v_fmac_f32_e32 v73, v62, v62
	v_fmac_f32_e32 v75, v64, v64
	v_add_f32_e32 v73, v73, v75
	v_mul_f32_e32 v75, v59, v59
	v_mul_f32_e32 v77, v61, v61
	v_fmac_f32_e32 v75, v58, v58
	v_fmac_f32_e32 v77, v60, v60
	v_add_f32_e32 v75, v75, v77
	v_add_f32_e32 v73, v73, v75
	v_mul_f32_e32 v75, v55, v55
	v_mul_f32_e32 v77, v57, v57
	v_fmac_f32_e32 v75, v54, v54
	v_fmac_f32_e32 v77, v56, v56
	v_add_f32_e32 v75, v75, v77
	v_add_f32_e32 v73, v73, v75
	v_mul_f32_e32 v75, v51, v51
	v_mul_f32_e32 v77, v53, v53
	v_fmac_f32_e32 v75, v50, v50
	v_fmac_f32_e32 v77, v52, v52
	v_add_f32_e32 v75, v75, v77
	v_add_f32_e32 v73, v73, v75
	ds_bpermute_b32 v75, v1, v73
	v_cvt_pk_f16_f32 v65, v64, v65
	v_cvt_pk_f16_f32 v64, v62, v63
	v_cvt_pk_f16_f32 v57, v56, v57
	v_cvt_pk_f16_f32 v56, v54, v55
	s_waitcnt lgkmcnt(0)
	v_add_f32_e32 v73, v73, v75
	ds_bpermute_b32 v75, v80, v73
	v_lshlrev_b64 v[90:91], 11, v[78:79]
	v_lshl_add_u64 v[90:91], v[68:69], 0, v[90:91]
	v_cvt_pk_f16_f32 v61, v60, v61
	v_cvt_pk_f16_f32 v60, v58, v59
	s_waitcnt lgkmcnt(0)
	v_add_f32_e32 v73, v73, v75
	ds_bpermute_b32 v75, v81, v73
	v_cvt_pk_f16_f32 v53, v52, v53
	v_cvt_pk_f16_f32 v52, v50, v51
	global_store_dwordx2 v[90:91], v[64:65], off nt
	global_store_dwordx2 v[90:91], v[60:61], off offset:512 nt
	s_waitcnt lgkmcnt(0)
	v_add_f32_e32 v73, v73, v75
	ds_bpermute_b32 v75, v82, v73
	global_store_dwordx2 v[90:91], v[56:57], off offset:1024 nt
	global_store_dwordx2 v[90:91], v[52:53], off offset:1536 nt
	s_waitcnt lgkmcnt(0)
	v_add_f32_e32 v62, v73, v75
	ds_bpermute_b32 v63, v83, v62
	s_waitcnt lgkmcnt(0)
	v_add_f32_e32 v54, v62, v63
	ds_bpermute_b32 v55, v84, v54
	s_and_saveexec_b64 s[14:15], vcc
	s_cbranch_execz .Lxc_102
	s_waitcnt lgkmcnt(0)
	v_add_f32_e32 v50, v54, v55
	v_cndmask_b32_e64 v52, 0, v50, s[4:5]
	v_lshlrev_b64 v[50:51], 6, v[78:79]
	v_lshl_add_u64 v[50:51], v[70:71], 0, v[50:51]
	global_store_dword v[50:51], v52, off
.Lxc_102:
	s_or_b64 exec, exec, s[14:15]
	s_and_saveexec_b64 s[14:15], s[12:13]
	s_cbranch_execz .Lxc_105
	v_mul_f32_e32 v50, v47, v47
	v_mul_f32_e32 v51, v49, v49
	v_fmac_f32_e32 v50, v46, v46
	v_fmac_f32_e32 v51, v48, v48
	v_add_f32_e32 v50, v50, v51
	v_mul_f32_e32 v51, v43, v43
	v_mul_f32_e32 v52, v45, v45
	v_fmac_f32_e32 v51, v42, v42
	v_fmac_f32_e32 v52, v44, v44
	v_add_f32_e32 v51, v51, v52
	v_add_f32_e32 v50, v51, v50
	v_mul_f32_e32 v51, v39, v39
	v_mul_f32_e32 v52, v41, v41
	v_fmac_f32_e32 v51, v38, v38
	v_fmac_f32_e32 v52, v40, v40
	v_add_f32_e32 v51, v51, v52
	v_add_f32_e32 v50, v51, v50
	v_mul_f32_e32 v51, v35, v35
	v_mul_f32_e32 v52, v37, v37
	v_fmac_f32_e32 v51, v34, v34
	v_fmac_f32_e32 v52, v36, v36
	v_add_f32_e32 v51, v51, v52
	v_add_f32_e32 v50, v51, v50
	ds_bpermute_b32 v51, v1, v50
	v_ashrrev_i32_e32 v73, 31, v72
	s_waitcnt lgkmcnt(0)
	v_add_f32_e32 v50, v50, v51
	ds_bpermute_b32 v51, v80, v50
	s_waitcnt lgkmcnt(0)
	v_add_f32_e32 v54, v50, v51
	ds_bpermute_b32 v55, v81, v54
	v_lshlrev_b64 v[50:51], 11, v[72:73]
	v_lshl_add_u64 v[52:53], v[68:69], 0, v[50:51]
	v_cvt_pk_f16_f32 v51, v48, v49
	v_cvt_pk_f16_f32 v50, v46, v47
	s_waitcnt lgkmcnt(0)
	v_add_f32_e32 v54, v54, v55
	ds_bpermute_b32 v55, v82, v54
	global_store_dwordx2 v[52:53], v[50:51], off nt
	v_cvt_pk_f16_f32 v51, v44, v45
	v_cvt_pk_f16_f32 v50, v42, v43
	global_store_dwordx2 v[52:53], v[50:51], off offset:512 nt
	s_waitcnt lgkmcnt(0)
	v_add_f32_e32 v56, v54, v55
	ds_bpermute_b32 v57, v83, v56
	v_cvt_pk_f16_f32 v55, v40, v41
	v_cvt_pk_f16_f32 v54, v38, v39
	global_store_dwordx2 v[52:53], v[54:55], off offset:1024 nt
	v_cvt_pk_f16_f32 v55, v36, v37
	s_waitcnt lgkmcnt(0)
	v_add_f32_e32 v50, v56, v57
	ds_bpermute_b32 v51, v84, v50
	v_cvt_pk_f16_f32 v54, v34, v35
	global_store_dwordx2 v[52:53], v[54:55], off offset:1536 nt
	s_and_b64 exec, exec, vcc
	s_cbranch_execz .Lxc_105
	s_waitcnt lgkmcnt(0)
	v_add_f32_e32 v50, v50, v51
	v_cndmask_b32_e64 v52, 0, v50, s[4:5]
	v_lshlrev_b64 v[50:51], 6, v[72:73]
	v_lshl_add_u64 v[50:51], v[70:71], 0, v[50:51]
	global_store_dword v[50:51], v52, off
; __device__ void p0_xconv(const Args& a) {
;     ...
;         for (int r = 0; r < 4; ++r) {
;             const int row = row0 + r * nwv;
;             if (row < MROWS) {
;                 float ss = 0.f;
; #pragma unroll
;                 for (int i = 0; i < 4; ++i) {
;                     const f32x4 x = v[r][i];
;                     ss += (x[0] * x[0] + x[1] * x[1]) + (x[2] * x[2] + x[3] * x[3]);
;                     f16x4 h; h[0] = (f16)x[0]; h[1] = (f16)x[1]; h[2] = (f16)x[2]; h[3] = (f16)x[3];
;                     *(f16x4*)(XH + (size_t)row * DM + i * 256 + lane * 4) = h;
;                 }
; #pragma unroll
;                 for (int o = 1; o < 64; o <<= 1) ss += __shfl_xor(ss, o);
;                 if (lane < 16) SS[(size_t)row * 16 + lane] = (lane == 0) ? ss : 0.f;
;             }
.Lxc_105:
	s_or_b64 exec, exec, s[14:15]
	s_and_saveexec_b64 s[12:13], s[10:11]
	s_cbranch_execz .Lxc_108
	v_mul_f32_e32 v50, v31, v31
	s_waitcnt lgkmcnt(0)
	v_mul_f32_e32 v51, v33, v33
	v_fmac_f32_e32 v50, v30, v30
	v_fmac_f32_e32 v51, v32, v32
	v_add_f32_e32 v50, v50, v51
	v_mul_f32_e32 v51, v27, v27
	v_mul_f32_e32 v52, v29, v29
	v_fmac_f32_e32 v51, v26, v26
	v_fmac_f32_e32 v52, v28, v28
	v_add_f32_e32 v51, v51, v52
	v_add_f32_e32 v50, v51, v50
	v_mul_f32_e32 v51, v23, v23
	v_mul_f32_e32 v52, v25, v25
	v_fmac_f32_e32 v51, v22, v22
	v_fmac_f32_e32 v52, v24, v24
	v_add_f32_e32 v51, v51, v52
	v_add_f32_e32 v50, v51, v50
	v_mul_f32_e32 v51, v19, v19
	v_mul_f32_e32 v52, v21, v21
	v_fmac_f32_e32 v51, v18, v18
	v_fmac_f32_e32 v52, v20, v20
	v_add_f32_e32 v51, v51, v52
	v_add_f32_e32 v50, v51, v50
	ds_bpermute_b32 v51, v1, v50
	v_ashrrev_i32_e32 v77, 31, v76
	s_waitcnt lgkmcnt(0)
	v_add_f32_e32 v50, v50, v51
	ds_bpermute_b32 v51, v80, v50
	s_waitcnt lgkmcnt(0)
	v_add_f32_e32 v54, v50, v51
	ds_bpermute_b32 v55, v81, v54
	v_lshlrev_b64 v[50:51], 11, v[76:77]
	v_lshl_add_u64 v[52:53], v[68:69], 0, v[50:51]
	v_cvt_pk_f16_f32 v51, v32, v33
	v_cvt_pk_f16_f32 v50, v30, v31
	s_waitcnt lgkmcnt(0)
	v_add_f32_e32 v54, v54, v55
	ds_bpermute_b32 v55, v82, v54
	global_store_dwordx2 v[52:53], v[50:51], off nt
	v_cvt_pk_f16_f32 v51, v28, v29
	v_cvt_pk_f16_f32 v50, v26, v27
	global_store_dwordx2 v[52:53], v[50:51], off offset:512 nt
	s_waitcnt lgkmcnt(0)
	v_add_f32_e32 v56, v54, v55
	ds_bpermute_b32 v57, v83, v56
	v_cvt_pk_f16_f32 v55, v24, v25
	v_cvt_pk_f16_f32 v54, v22, v23
	global_store_dwordx2 v[52:53], v[54:55], off offset:1024 nt
	v_cvt_pk_f16_f32 v55, v20, v21
	s_waitcnt lgkmcnt(0)
	v_add_f32_e32 v50, v56, v57
	ds_bpermute_b32 v51, v84, v50
	v_cvt_pk_f16_f32 v54, v18, v19
	global_store_dwordx2 v[52:53], v[54:55], off offset:1536 nt
	s_and_b64 exec, exec, vcc
	s_cbranch_execz .Lxc_108
	s_waitcnt lgkmcnt(0)
	v_add_f32_e32 v50, v50, v51
	v_cndmask_b32_e64 v52, 0, v50, s[4:5]
	v_lshlrev_b64 v[50:51], 6, v[76:77]
	v_lshl_add_u64 v[50:51], v[70:71], 0, v[50:51]
	global_store_dword v[50:51], v52, off
.Lxc_108:
	s_or_b64 exec, exec, s[12:13]
	s_and_saveexec_b64 s[10:11], s[6:7]
	s_cbranch_execz .Lxc_93
	v_mul_f32_e32 v50, v15, v15
	s_waitcnt lgkmcnt(0)
	v_mul_f32_e32 v51, v17, v17
	v_fmac_f32_e32 v50, v14, v14
	v_fmac_f32_e32 v51, v16, v16
	v_add_f32_e32 v50, v50, v51
	v_mul_f32_e32 v51, v11, v11
	v_mul_f32_e32 v52, v13, v13
	v_fmac_f32_e32 v51, v10, v10
	v_fmac_f32_e32 v52, v12, v12
	v_add_f32_e32 v51, v51, v52
	v_add_f32_e32 v50, v51, v50
	v_mul_f32_e32 v51, v7, v7
	v_mul_f32_e32 v52, v9, v9
	v_fmac_f32_e32 v51, v6, v6
	v_fmac_f32_e32 v52, v8, v8
	v_add_f32_e32 v51, v51, v52
	v_add_f32_e32 v50, v51, v50
	v_mul_f32_e32 v51, v3, v3
	v_mul_f32_e32 v52, v5, v5
	v_fmac_f32_e32 v51, v2, v2
	v_fmac_f32_e32 v52, v4, v4
	v_add_f32_e32 v51, v51, v52
	v_add_f32_e32 v50, v51, v50
	ds_bpermute_b32 v51, v1, v50
	v_ashrrev_i32_e32 v75, 31, v74
	s_waitcnt lgkmcnt(0)
	v_add_f32_e32 v50, v50, v51
	ds_bpermute_b32 v51, v80, v50
	s_waitcnt lgkmcnt(0)
	v_add_f32_e32 v54, v50, v51
	ds_bpermute_b32 v55, v81, v54
	v_lshlrev_b64 v[50:51], 11, v[74:75]
	v_lshl_add_u64 v[52:53], v[68:69], 0, v[50:51]
	v_cvt_pk_f16_f32 v51, v16, v17
	v_cvt_pk_f16_f32 v50, v14, v15
	s_waitcnt lgkmcnt(0)
	v_add_f32_e32 v54, v54, v55
	ds_bpermute_b32 v55, v82, v54
	global_store_dwordx2 v[52:53], v[50:51], off nt
	v_cvt_pk_f16_f32 v51, v12, v13
	v_cvt_pk_f16_f32 v50, v10, v11
	global_store_dwordx2 v[52:53], v[50:51], off offset:512 nt
	s_waitcnt lgkmcnt(0)
	v_add_f32_e32 v56, v54, v55
	ds_bpermute_b32 v57, v83, v56
	v_cvt_pk_f16_f32 v55, v8, v9
	v_cvt_pk_f16_f32 v54, v6, v7
	global_store_dwordx2 v[52:53], v[54:55], off offset:1024 nt
	v_cvt_pk_f16_f32 v55, v4, v5
	s_waitcnt lgkmcnt(0)
	v_add_f32_e32 v50, v56, v57
	ds_bpermute_b32 v51, v84, v50
	v_cvt_pk_f16_f32 v54, v2, v3
	global_store_dwordx2 v[52:53], v[54:55], off offset:1536 nt
	s_and_b64 exec, exec, vcc
	s_cbranch_execz .Lxc_93
	s_waitcnt lgkmcnt(0)
	v_add_f32_e32 v50, v50, v51
	v_cndmask_b32_e64 v52, 0, v50, s[4:5]
	v_lshlrev_b64 v[50:51], 6, v[74:75]
	v_lshl_add_u64 v[50:51], v[70:71], 0, v[50:51]
	global_store_dword v[50:51], v52, off
	s_branch .Lxc_93

; __device__ void p0_xconv(const Args& a) {
;     ...
;     const int lane = tid_ & 63, wv = tid_ >> 6;
;     const int nwv = (int)gridDim.x * 8;
;     for (int row0 = (int)blockIdx.x * 8 + wv; row0 < MROWS; row0 += 4 * nwv) {
;         f32x4 v[4][4];
; #pragma unroll
;         for (int r = 0; r < 4; ++r) {
;             const int row = row0 + r * nwv;
;             if (row < MROWS) {
;                 const float* src = (row < ROWS_PROMPT) ? a.x_prompt + (size_t)row * DM : a.x_sample + (size_t)(row - ROWS_PROMPT) * DM;
; #pragma unroll
;                 for (int i = 0; i < 4; ++i) v[r][i] = __builtin_nontemporal_load((const f32x4*)(src + i * 256 + lane * 4));
;             }
;         }
; #pragma unroll
;         for (int r = 0; r < 4; ++r) {
;             const int row = row0 + r * nwv;
;             if (row < MROWS) {
;                 float ss = 0.f;
; #pragma unroll
;                 for (int i = 0; i < 4; ++i) {
;                     const f32x4 x = v[r][i];
;                     ss += (x[0] * x[0] + x[1] * x[1]) + (x[2] * x[2] + x[3] * x[3]);
;                     f16x4 h; h[0] = (f16)x[0]; h[1] = (f16)x[1]; h[2] = (f16)x[2]; h[3] = (f16)x[3];
;                     *(f16x4*)(XH + (size_t)row * DM + i * 256 + lane * 4) = h;
;                 }
; #pragma unroll
;                 for (int o = 1; o < 64; o <<= 1) ss += __shfl_xor(ss, o);
;                 if (lane < 16) SS[(size_t)row * 16 + lane] = (lane == 0) ? ss : 0.f;
.Lpw_x:
	s_barrier
	v_and_b32_e32 v136, 63, v0
	v_lshrrev_b32_e32 v137, 6, v0
	s_nop 0
	v_readfirstlane_b32 s3, v137
	s_nop 3
	s_lshl_b32 s4, s2, 2
	s_add_i32 s3, s3, s4
	s_add_i32 s3, s3, -4
	s_mov_b64 s[12:13], 1
	v_xor_b32_e32 v130, 1, v136
	v_lshlrev_b32_e32 v130, 2, v130
	v_xor_b32_e32 v131, 2, v136
	v_lshlrev_b32_e32 v131, 2, v131
	v_xor_b32_e32 v132, 4, v136
	v_lshlrev_b32_e32 v132, 2, v132
	v_xor_b32_e32 v133, 8, v136
	v_lshlrev_b32_e32 v133, 2, v133
	v_xor_b32_e32 v134, 16, v136
	v_lshlrev_b32_e32 v134, 2, v134
	v_xor_b32_e32 v135, 32, v136
	v_lshlrev_b32_e32 v135, 2, v135
	v_lshlrev_b32_e32 v140, 4, v136
	v_lshlrev_b32_e32 v144, 3, v136
	v_lshlrev_b32_e32 v186, 2, v136
	v_lshlrev_b32_e32 v141, 4, v136
	v_add_u32_e32 v141, 0x400000, v141
	v_lshlrev_b32_e32 v145, 3, v136
	v_add_u32_e32 v145, 0x200000, v145
	v_lshlrev_b32_e32 v187, 2, v136
	v_add_u32_e32 v187, 0x10000, v187
	v_lshlrev_b32_e32 v142, 4, v136
	v_add_u32_e32 v142, 0x800000, v142
	v_lshlrev_b32_e32 v146, 3, v136
	v_add_u32_e32 v146, 0x400000, v146
	v_lshlrev_b32_e32 v188, 2, v136
	v_add_u32_e32 v188, 0x20000, v188
	v_lshlrev_b32_e32 v143, 4, v136
	v_add_u32_e32 v143, 0xc00000, v143
	v_lshlrev_b32_e32 v147, 3, v136
	v_add_u32_e32 v147, 0x600000, v147
	v_lshlrev_b32_e32 v189, 2, v136
	v_add_u32_e32 v189, 0x30000, v189
	s_add_i32 s6, s3, 0x4000
	s_lshl_b32 s6, s6, 12
	s_add_u32 s4, s18, s6
	s_addc_u32 s5, s19, 0
	global_load_dwordx4 v[2:5], v140, s[4:5] nt
	global_load_dwordx4 v[6:9], v140, s[4:5] offset:1024 nt
	global_load_dwordx4 v[10:13], v140, s[4:5] offset:2048 nt
	global_load_dwordx4 v[14:17], v140, s[4:5] offset:3072 nt
	global_load_dwordx4 v[18:21], v141, s[4:5] nt
	global_load_dwordx4 v[22:25], v141, s[4:5] offset:1024 nt
	global_load_dwordx4 v[26:29], v141, s[4:5] offset:2048 nt
	global_load_dwordx4 v[30:33], v141, s[4:5] offset:3072 nt
	global_load_dwordx4 v[34:37], v142, s[4:5] nt
	global_load_dwordx4 v[38:41], v142, s[4:5] offset:1024 nt
	global_load_dwordx4 v[42:45], v142, s[4:5] offset:2048 nt
	global_load_dwordx4 v[46:49], v142, s[4:5] offset:3072 nt
	global_load_dwordx4 v[50:53], v143, s[4:5] nt
	global_load_dwordx4 v[54:57], v143, s[4:5] offset:1024 nt
	global_load_dwordx4 v[58:61], v143, s[4:5] offset:2048 nt
	global_load_dwordx4 v[62:65], v143, s[4:5] offset:3072 nt
	s_add_i32 s6, s3, 0x5000
	s_lshl_b32 s6, s6, 12
	s_add_u32 s4, s18, s6
	s_addc_u32 s5, s19, 0
	global_load_dwordx4 v[66:69], v140, s[4:5] nt
	global_load_dwordx4 v[70:73], v140, s[4:5] offset:1024 nt
	global_load_dwordx4 v[74:77], v140, s[4:5] offset:2048 nt
	global_load_dwordx4 v[78:81], v140, s[4:5] offset:3072 nt
	global_load_dwordx4 v[82:85], v141, s[4:5] nt
	global_load_dwordx4 v[86:89], v141, s[4:5] offset:1024 nt
	global_load_dwordx4 v[90:93], v141, s[4:5] offset:2048 nt
	global_load_dwordx4 v[94:97], v141, s[4:5] offset:3072 nt
	global_load_dwordx4 v[98:101], v142, s[4:5] nt
	global_load_dwordx4 v[102:105], v142, s[4:5] offset:1024 nt
	global_load_dwordx4 v[106:109], v142, s[4:5] offset:2048 nt
	global_load_dwordx4 v[110:113], v142, s[4:5] offset:3072 nt
	global_load_dwordx4 v[114:117], v143, s[4:5] nt
	global_load_dwordx4 v[118:121], v143, s[4:5] offset:1024 nt
	global_load_dwordx4 v[122:125], v143, s[4:5] offset:2048 nt
	global_load_dwordx4 v[126:129], v143, s[4:5] offset:3072 nt
	s_waitcnt vmcnt(16)
	s_add_i32 s6, s3, 0x8000
	s_lshl_b32 s7, s6, 11
	s_add_u32 s10, s40, s7
	s_addc_u32 s11, s41, 0
	s_lshl_b32 s7, s6, 6
	s_add_u32 s6, s40, s7
	s_addc_u32 s7, s41, 0
	s_add_u32 s6, s6, 0x1f800000
	s_addc_u32 s7, s7, 0
	v_mul_f32_e32 v150, v3, v3
	v_mul_f32_e32 v151, v5, v5
	v_fmac_f32_e32 v150, v2, v2
	v_fmac_f32_e32 v151, v4, v4
	v_add_f32_e32 v160, v150, v151
	v_cvt_pk_f16_f32 v170, v2, v3
	v_cvt_pk_f16_f32 v171, v4, v5
	v_mul_f32_e32 v150, v7, v7
	v_mul_f32_e32 v151, v9, v9
	v_fmac_f32_e32 v150, v6, v6
	v_fmac_f32_e32 v151, v8, v8
	v_add_f32_e32 v152, v150, v151
	v_add_f32_e32 v160, v160, v152
	v_cvt_pk_f16_f32 v172, v6, v7
	v_cvt_pk_f16_f32 v173, v8, v9
	v_mul_f32_e32 v150, v11, v11
	v_mul_f32_e32 v151, v13, v13
	v_fmac_f32_e32 v150, v10, v10
	v_fmac_f32_e32 v151, v12, v12
	v_add_f32_e32 v152, v150, v151
	v_add_f32_e32 v160, v160, v152
	v_cvt_pk_f16_f32 v174, v10, v11
	v_cvt_pk_f16_f32 v175, v12, v13
	v_mul_f32_e32 v150, v15, v15
	v_mul_f32_e32 v151, v17, v17
	v_fmac_f32_e32 v150, v14, v14
	v_fmac_f32_e32 v151, v16, v16
	v_add_f32_e32 v152, v150, v151
	v_add_f32_e32 v160, v160, v152
	v_cvt_pk_f16_f32 v176, v14, v15
	v_cvt_pk_f16_f32 v177, v16, v17
	global_store_dwordx2 v144, v[170:171], s[10:11] nt
	global_store_dwordx2 v144, v[172:173], s[10:11] offset:512 nt
	global_store_dwordx2 v144, v[174:175], s[10:11] offset:1024 nt
	global_store_dwordx2 v144, v[176:177], s[10:11] offset:1536 nt
	v_mul_f32_e32 v150, v19, v19
	v_mul_f32_e32 v151, v21, v21
	v_fmac_f32_e32 v150, v18, v18
	v_fmac_f32_e32 v151, v20, v20
	v_add_f32_e32 v161, v150, v151
	v_cvt_pk_f16_f32 v178, v18, v19
	v_cvt_pk_f16_f32 v179, v20, v21
	v_mul_f32_e32 v150, v23, v23
	v_mul_f32_e32 v151, v25, v25
	v_fmac_f32_e32 v150, v22, v22
	v_fmac_f32_e32 v151, v24, v24
	v_add_f32_e32 v152, v150, v151
	v_add_f32_e32 v161, v161, v152
	v_cvt_pk_f16_f32 v180, v22, v23
	v_cvt_pk_f16_f32 v181, v24, v25
	v_mul_f32_e32 v150, v27, v27
	v_mul_f32_e32 v151, v29, v29
	v_fmac_f32_e32 v150, v26, v26
	v_fmac_f32_e32 v151, v28, v28
	v_add_f32_e32 v152, v150, v151
	v_add_f32_e32 v161, v161, v152
	v_cvt_pk_f16_f32 v182, v26, v27
	v_cvt_pk_f16_f32 v183, v28, v29
	v_mul_f32_e32 v150, v31, v31
	v_mul_f32_e32 v151, v33, v33
	v_fmac_f32_e32 v150, v30, v30
	v_fmac_f32_e32 v151, v32, v32
	v_add_f32_e32 v152, v150, v151
	v_add_f32_e32 v161, v161, v152
; __device__ void p0_xconv(const Args& a) {
;     ...
;         for (int r = 0; r < 4; ++r) {
;             const int row = row0 + r * nwv;
;             if (row < MROWS) {
;                 float ss = 0.f;
; #pragma unroll
;                 for (int i = 0; i < 4; ++i) {
;                     const f32x4 x = v[r][i];
;                     ss += (x[0] * x[0] + x[1] * x[1]) + (x[2] * x[2] + x[3] * x[3]);
;                     f16x4 h; h[0] = (f16)x[0]; h[1] = (f16)x[1]; h[2] = (f16)x[2]; h[3] = (f16)x[3];
;                     *(f16x4*)(XH + (size_t)row * DM + i * 256 + lane * 4) = h;
;                 }
; #pragma unroll
;                 for (int o = 1; o < 64; o <<= 1) ss += __shfl_xor(ss, o);
;                 if (lane < 16) SS[(size_t)row * 16 + lane] = (lane == 0) ? ss : 0.f;
	v_cvt_pk_f16_f32 v184, v30, v31
	v_cvt_pk_f16_f32 v185, v32, v33
	global_store_dwordx2 v145, v[178:179], s[10:11] nt
	global_store_dwordx2 v145, v[180:181], s[10:11] offset:512 nt
	global_store_dwordx2 v145, v[182:183], s[10:11] offset:1024 nt
	global_store_dwordx2 v145, v[184:185], s[10:11] offset:1536 nt
	v_mul_f32_e32 v150, v35, v35
	v_mul_f32_e32 v151, v37, v37
	v_fmac_f32_e32 v150, v34, v34
	v_fmac_f32_e32 v151, v36, v36
	v_add_f32_e32 v162, v150, v151
	v_cvt_pk_f16_f32 v170, v34, v35
	v_cvt_pk_f16_f32 v171, v36, v37
	v_mul_f32_e32 v150, v39, v39
	v_mul_f32_e32 v151, v41, v41
	v_fmac_f32_e32 v150, v38, v38
	v_fmac_f32_e32 v151, v40, v40
	v_add_f32_e32 v152, v150, v151
	v_add_f32_e32 v162, v162, v152
	v_cvt_pk_f16_f32 v172, v38, v39
	v_cvt_pk_f16_f32 v173, v40, v41
	v_mul_f32_e32 v150, v43, v43
	v_mul_f32_e32 v151, v45, v45
	v_fmac_f32_e32 v150, v42, v42
	v_fmac_f32_e32 v151, v44, v44
	v_add_f32_e32 v152, v150, v151
	v_add_f32_e32 v162, v162, v152
	v_cvt_pk_f16_f32 v174, v42, v43
	v_cvt_pk_f16_f32 v175, v44, v45
	v_mul_f32_e32 v150, v47, v47
	v_mul_f32_e32 v151, v49, v49
	v_fmac_f32_e32 v150, v46, v46
	v_fmac_f32_e32 v151, v48, v48
	v_add_f32_e32 v152, v150, v151
	v_add_f32_e32 v162, v162, v152
	v_cvt_pk_f16_f32 v176, v46, v47
	v_cvt_pk_f16_f32 v177, v48, v49
	global_store_dwordx2 v146, v[170:171], s[10:11] nt
	global_store_dwordx2 v146, v[172:173], s[10:11] offset:512 nt
	global_store_dwordx2 v146, v[174:175], s[10:11] offset:1024 nt
	global_store_dwordx2 v146, v[176:177], s[10:11] offset:1536 nt
	v_mul_f32_e32 v150, v51, v51
	v_mul_f32_e32 v151, v53, v53
	v_fmac_f32_e32 v150, v50, v50
	v_fmac_f32_e32 v151, v52, v52
	v_add_f32_e32 v163, v150, v151
	v_cvt_pk_f16_f32 v178, v50, v51
	v_cvt_pk_f16_f32 v179, v52, v53
	v_mul_f32_e32 v150, v55, v55
	v_mul_f32_e32 v151, v57, v57
	v_fmac_f32_e32 v150, v54, v54
	v_fmac_f32_e32 v151, v56, v56
	v_add_f32_e32 v152, v150, v151
	v_add_f32_e32 v163, v163, v152
	v_cvt_pk_f16_f32 v180, v54, v55
	v_cvt_pk_f16_f32 v181, v56, v57
	v_mul_f32_e32 v150, v59, v59
	v_mul_f32_e32 v151, v61, v61
	v_fmac_f32_e32 v150, v58, v58
	v_fmac_f32_e32 v151, v60, v60
	v_add_f32_e32 v152, v150, v151
	v_add_f32_e32 v163, v163, v152
	v_cvt_pk_f16_f32 v182, v58, v59
	v_cvt_pk_f16_f32 v183, v60, v61
	v_mul_f32_e32 v150, v63, v63
	v_mul_f32_e32 v151, v65, v65
	v_fmac_f32_e32 v150, v62, v62
	v_fmac_f32_e32 v151, v64, v64
	v_add_f32_e32 v152, v150, v151
	v_add_f32_e32 v163, v163, v152
	v_cvt_pk_f16_f32 v184, v62, v63
	v_cvt_pk_f16_f32 v185, v64, v65
	global_store_dwordx2 v147, v[178:179], s[10:11] nt
	global_store_dwordx2 v147, v[180:181], s[10:11] offset:512 nt
	global_store_dwordx2 v147, v[182:183], s[10:11] offset:1024 nt
	global_store_dwordx2 v147, v[184:185], s[10:11] offset:1536 nt
	ds_bpermute_b32 v164, v130, v160
	ds_bpermute_b32 v165, v130, v161
	ds_bpermute_b32 v166, v130, v162
	ds_bpermute_b32 v167, v130, v163
	s_waitcnt lgkmcnt(0)
	v_add_f32_e32 v160, v160, v164
	v_add_f32_e32 v161, v161, v165
	v_add_f32_e32 v162, v162, v166
	v_add_f32_e32 v163, v163, v167
	ds_bpermute_b32 v164, v131, v160
	ds_bpermute_b32 v165, v131, v161
	ds_bpermute_b32 v166, v131, v162
	ds_bpermute_b32 v167, v131, v163
	s_waitcnt lgkmcnt(0)
	v_add_f32_e32 v160, v160, v164
	v_add_f32_e32 v161, v161, v165
	v_add_f32_e32 v162, v162, v166
	v_add_f32_e32 v163, v163, v167
	ds_bpermute_b32 v164, v132, v160
	ds_bpermute_b32 v165, v132, v161
	ds_bpermute_b32 v166, v132, v162
	ds_bpermute_b32 v167, v132, v163
	s_waitcnt lgkmcnt(0)
	v_add_f32_e32 v160, v160, v164
	v_add_f32_e32 v161, v161, v165
	v_add_f32_e32 v162, v162, v166
	v_add_f32_e32 v163, v163, v167
	ds_bpermute_b32 v164, v133, v160
	ds_bpermute_b32 v165, v133, v161
	ds_bpermute_b32 v166, v133, v162
	ds_bpermute_b32 v167, v133, v163
	s_waitcnt lgkmcnt(0)
	v_add_f32_e32 v160, v160, v164
	v_add_f32_e32 v161, v161, v165
	v_add_f32_e32 v162, v162, v166
	v_add_f32_e32 v163, v163, v167
	ds_bpermute_b32 v164, v134, v160
	ds_bpermute_b32 v165, v134, v161
	ds_bpermute_b32 v166, v134, v162
	ds_bpermute_b32 v167, v134, v163
	s_waitcnt lgkmcnt(0)
	v_add_f32_e32 v160, v160, v164
	v_add_f32_e32 v161, v161, v165
	v_add_f32_e32 v162, v162, v166
	v_add_f32_e32 v163, v163, v167
	ds_bpermute_b32 v164, v135, v160
	ds_bpermute_b32 v165, v135, v161
	ds_bpermute_b32 v166, v135, v162
	ds_bpermute_b32 v167, v135, v163
	s_waitcnt lgkmcnt(0)
	v_add_f32_e32 v160, v160, v164
	v_add_f32_e32 v161, v161, v165
	v_add_f32_e32 v162, v162, v166
	v_add_f32_e32 v163, v163, v167
	v_cndmask_b32_e64 v164, 0, v160, s[12:13]
	v_cndmask_b32_e64 v165, 0, v161, s[12:13]
	v_cndmask_b32_e64 v166, 0, v162, s[12:13]
	v_cndmask_b32_e64 v167, 0, v163, s[12:13]
	s_mov_b64 exec, 0xffff
	global_store_dword v186, v164, s[6:7]
	global_store_dword v187, v165, s[6:7]
	global_store_dword v188, v166, s[6:7]
	global_store_dword v189, v167, s[6:7]
	s_mov_b64 exec, -1
	s_barrier
; __device__ void p0_xconv(const Args& a) {
;     ...
;         for (int r = 0; r < 4; ++r) {
;             const int row = row0 + r * nwv;
;             if (row < MROWS) {
;                 const float* src = (row < ROWS_PROMPT) ? a.x_prompt + (size_t)row * DM : a.x_sample + (size_t)(row - ROWS_PROMPT) * DM;
; #pragma unroll
;                 for (int i = 0; i < 4; ++i) v[r][i] = __builtin_nontemporal_load((const f32x4*)(src + i * 256 + lane * 4));
;             }
;         }
; #pragma unroll
;         for (int r = 0; r < 4; ++r) {
;             const int row = row0 + r * nwv;
;             if (row < MROWS) {
;                 float ss = 0.f;
; #pragma unroll
;                 for (int i = 0; i < 4; ++i) {
;                     const f32x4 x = v[r][i];
;                     ss += (x[0] * x[0] + x[1] * x[1]) + (x[2] * x[2] + x[3] * x[3]);
;                     f16x4 h; h[0] = (f16)x[0]; h[1] = (f16)x[1]; h[2] = (f16)x[2]; h[3] = (f16)x[3];
;                     *(f16x4*)(XH + (size_t)row * DM + i * 256 + lane * 4) = h;
;                 }
; #pragma unroll
;                 for (int o = 1; o < 64; o <<= 1) ss += __shfl_xor(ss, o);
;                 if (lane < 16) SS[(size_t)row * 16 + lane] = (lane == 0) ? ss : 0.f;
	s_add_i32 s6, s3, 0x6000
	s_lshl_b32 s6, s6, 12
	s_add_u32 s4, s18, s6
	s_addc_u32 s5, s19, 0
	global_load_dwordx4 v[2:5], v140, s[4:5] nt
	global_load_dwordx4 v[6:9], v140, s[4:5] offset:1024 nt
	global_load_dwordx4 v[10:13], v140, s[4:5] offset:2048 nt
	global_load_dwordx4 v[14:17], v140, s[4:5] offset:3072 nt
	global_load_dwordx4 v[18:21], v141, s[4:5] nt
	global_load_dwordx4 v[22:25], v141, s[4:5] offset:1024 nt
	global_load_dwordx4 v[26:29], v141, s[4:5] offset:2048 nt
	global_load_dwordx4 v[30:33], v141, s[4:5] offset:3072 nt
	global_load_dwordx4 v[34:37], v142, s[4:5] nt
	global_load_dwordx4 v[38:41], v142, s[4:5] offset:1024 nt
	global_load_dwordx4 v[42:45], v142, s[4:5] offset:2048 nt
	global_load_dwordx4 v[46:49], v142, s[4:5] offset:3072 nt
	global_load_dwordx4 v[50:53], v143, s[4:5] nt
	global_load_dwordx4 v[54:57], v143, s[4:5] offset:1024 nt
	global_load_dwordx4 v[58:61], v143, s[4:5] offset:2048 nt
	global_load_dwordx4 v[62:65], v143, s[4:5] offset:3072 nt
	s_waitcnt vmcnt(36)
	s_add_i32 s6, s3, 0x9000
	s_lshl_b32 s7, s6, 11
	s_add_u32 s10, s40, s7
	s_addc_u32 s11, s41, 0
	s_lshl_b32 s7, s6, 6
	s_add_u32 s6, s40, s7
	s_addc_u32 s7, s41, 0
	s_add_u32 s6, s6, 0x1f800000
	s_addc_u32 s7, s7, 0
	v_mul_f32_e32 v150, v67, v67
	v_mul_f32_e32 v151, v69, v69
	v_fmac_f32_e32 v150, v66, v66
	v_fmac_f32_e32 v151, v68, v68
	v_add_f32_e32 v160, v150, v151
	v_cvt_pk_f16_f32 v170, v66, v67
	v_cvt_pk_f16_f32 v171, v68, v69
	v_mul_f32_e32 v150, v71, v71
	v_mul_f32_e32 v151, v73, v73
	v_fmac_f32_e32 v150, v70, v70
	v_fmac_f32_e32 v151, v72, v72
	v_add_f32_e32 v152, v150, v151
	v_add_f32_e32 v160, v160, v152
	v_cvt_pk_f16_f32 v172, v70, v71
	v_cvt_pk_f16_f32 v173, v72, v73
	v_mul_f32_e32 v150, v75, v75
	v_mul_f32_e32 v151, v77, v77
	v_fmac_f32_e32 v150, v74, v74
	v_fmac_f32_e32 v151, v76, v76
	v_add_f32_e32 v152, v150, v151
	v_add_f32_e32 v160, v160, v152
	v_cvt_pk_f16_f32 v174, v74, v75
	v_cvt_pk_f16_f32 v175, v76, v77
	v_mul_f32_e32 v150, v79, v79
	v_mul_f32_e32 v151, v81, v81
	v_fmac_f32_e32 v150, v78, v78
	v_fmac_f32_e32 v151, v80, v80
	v_add_f32_e32 v152, v150, v151
	v_add_f32_e32 v160, v160, v152
	v_cvt_pk_f16_f32 v176, v78, v79
	v_cvt_pk_f16_f32 v177, v80, v81
	global_store_dwordx2 v144, v[170:171], s[10:11] nt
	global_store_dwordx2 v144, v[172:173], s[10:11] offset:512 nt
	global_store_dwordx2 v144, v[174:175], s[10:11] offset:1024 nt
	global_store_dwordx2 v144, v[176:177], s[10:11] offset:1536 nt
	v_mul_f32_e32 v150, v83, v83
	v_mul_f32_e32 v151, v85, v85
	v_fmac_f32_e32 v150, v82, v82
	v_fmac_f32_e32 v151, v84, v84
	v_add_f32_e32 v161, v150, v151
	v_cvt_pk_f16_f32 v178, v82, v83
	v_cvt_pk_f16_f32 v179, v84, v85
	v_mul_f32_e32 v150, v87, v87
	v_mul_f32_e32 v151, v89, v89
	v_fmac_f32_e32 v150, v86, v86
	v_fmac_f32_e32 v151, v88, v88
	v_add_f32_e32 v152, v150, v151
	v_add_f32_e32 v161, v161, v152
	v_cvt_pk_f16_f32 v180, v86, v87
	v_cvt_pk_f16_f32 v181, v88, v89
	v_mul_f32_e32 v150, v91, v91
	v_mul_f32_e32 v151, v93, v93
	v_fmac_f32_e32 v150, v90, v90
	v_fmac_f32_e32 v151, v92, v92
	v_add_f32_e32 v152, v150, v151
	v_add_f32_e32 v161, v161, v152
	v_cvt_pk_f16_f32 v182, v90, v91
	v_cvt_pk_f16_f32 v183, v92, v93
	v_mul_f32_e32 v150, v95, v95
	v_mul_f32_e32 v151, v97, v97
	v_fmac_f32_e32 v150, v94, v94
	v_fmac_f32_e32 v151, v96, v96
	v_add_f32_e32 v152, v150, v151
	v_add_f32_e32 v161, v161, v152
	v_cvt_pk_f16_f32 v184, v94, v95
	v_cvt_pk_f16_f32 v185, v96, v97
	global_store_dwordx2 v145, v[178:179], s[10:11] nt
	global_store_dwordx2 v145, v[180:181], s[10:11] offset:512 nt
	global_store_dwordx2 v145, v[182:183], s[10:11] offset:1024 nt
	global_store_dwordx2 v145, v[184:185], s[10:11] offset:1536 nt
	v_mul_f32_e32 v150, v99, v99
	v_mul_f32_e32 v151, v101, v101
	v_fmac_f32_e32 v150, v98, v98
	v_fmac_f32_e32 v151, v100, v100
	v_add_f32_e32 v162, v150, v151
	v_cvt_pk_f16_f32 v170, v98, v99
	v_cvt_pk_f16_f32 v171, v100, v101
	v_mul_f32_e32 v150, v103, v103
	v_mul_f32_e32 v151, v105, v105
	v_fmac_f32_e32 v150, v102, v102
	v_fmac_f32_e32 v151, v104, v104
	v_add_f32_e32 v152, v150, v151
	v_add_f32_e32 v162, v162, v152
	v_cvt_pk_f16_f32 v172, v102, v103
	v_cvt_pk_f16_f32 v173, v104, v105
	v_mul_f32_e32 v150, v107, v107
	v_mul_f32_e32 v151, v109, v109
	v_fmac_f32_e32 v150, v106, v106
	v_fmac_f32_e32 v151, v108, v108
	v_add_f32_e32 v152, v150, v151
	v_add_f32_e32 v162, v162, v152
	v_cvt_pk_f16_f32 v174, v106, v107
	v_cvt_pk_f16_f32 v175, v108, v109
	v_mul_f32_e32 v150, v111, v111
	v_mul_f32_e32 v151, v113, v113
	v_fmac_f32_e32 v150, v110, v110
	v_fmac_f32_e32 v151, v112, v112
	v_add_f32_e32 v152, v150, v151
	v_add_f32_e32 v162, v162, v152
	v_cvt_pk_f16_f32 v176, v110, v111
	v_cvt_pk_f16_f32 v177, v112, v113
	global_store_dwordx2 v146, v[170:171], s[10:11] nt
	global_store_dwordx2 v146, v[172:173], s[10:11] offset:512 nt
	global_store_dwordx2 v146, v[174:175], s[10:11] offset:1024 nt
	global_store_dwordx2 v146, v[176:177], s[10:11] offset:1536 nt
	v_mul_f32_e32 v150, v115, v115
	v_mul_f32_e32 v151, v117, v117
	v_fmac_f32_e32 v150, v114, v114
	v_fmac_f32_e32 v151, v116, v116
	v_add_f32_e32 v163, v150, v151
	v_cvt_pk_f16_f32 v178, v114, v115
	v_cvt_pk_f16_f32 v179, v116, v117
	v_mul_f32_e32 v150, v119, v119
	v_mul_f32_e32 v151, v121, v121
	v_fmac_f32_e32 v150, v118, v118
	v_fmac_f32_e32 v151, v120, v120
	v_add_f32_e32 v152, v150, v151
	v_add_f32_e32 v163, v163, v152
	v_cvt_pk_f16_f32 v180, v118, v119
	v_cvt_pk_f16_f32 v181, v120, v121
	v_mul_f32_e32 v150, v123, v123
	v_mul_f32_e32 v151, v125, v125
	v_fmac_f32_e32 v150, v122, v122
	v_fmac_f32_e32 v151, v124, v124
	v_add_f32_e32 v152, v150, v151
	v_add_f32_e32 v163, v163, v152
	v_cvt_pk_f16_f32 v182, v122, v123
	v_cvt_pk_f16_f32 v183, v124, v125
	v_mul_f32_e32 v150, v127, v127
	v_mul_f32_e32 v151, v129, v129
	v_fmac_f32_e32 v150, v126, v126
	v_fmac_f32_e32 v151, v128, v128
	v_add_f32_e32 v152, v150, v151
	v_add_f32_e32 v163, v163, v152
	v_cvt_pk_f16_f32 v184, v126, v127
	v_cvt_pk_f16_f32 v185, v128, v129
	global_store_dwordx2 v147, v[178:179], s[10:11] nt
	global_store_dwordx2 v147, v[180:181], s[10:11] offset:512 nt
	global_store_dwordx2 v147, v[182:183], s[10:11] offset:1024 nt
	global_store_dwordx2 v147, v[184:185], s[10:11] offset:1536 nt
	ds_bpermute_b32 v164, v130, v160
	ds_bpermute_b32 v165, v130, v161
	ds_bpermute_b32 v166, v130, v162
	ds_bpermute_b32 v167, v130, v163
	s_waitcnt lgkmcnt(0)
; __device__ void p0_xconv(const Args& a) {
;     ...
;         for (int r = 0; r < 4; ++r) {
;             const int row = row0 + r * nwv;
;             if (row < MROWS) {
;                 const float* src = (row < ROWS_PROMPT) ? a.x_prompt + (size_t)row * DM : a.x_sample + (size_t)(row - ROWS_PROMPT) * DM;
; #pragma unroll
;                 for (int i = 0; i < 4; ++i) v[r][i] = __builtin_nontemporal_load((const f32x4*)(src + i * 256 + lane * 4));
;             }
;         }
; #pragma unroll
;         for (int r = 0; r < 4; ++r) {
;             const int row = row0 + r * nwv;
;             if (row < MROWS) {
;                 float ss = 0.f;
; #pragma unroll
;                 for (int i = 0; i < 4; ++i) {
;                     const f32x4 x = v[r][i];
;                     ss += (x[0] * x[0] + x[1] * x[1]) + (x[2] * x[2] + x[3] * x[3]);
;                     f16x4 h; h[0] = (f16)x[0]; h[1] = (f16)x[1]; h[2] = (f16)x[2]; h[3] = (f16)x[3];
;                     *(f16x4*)(XH + (size_t)row * DM + i * 256 + lane * 4) = h;
;                 }
; #pragma unroll
;                 for (int o = 1; o < 64; o <<= 1) ss += __shfl_xor(ss, o);
;                 if (lane < 16) SS[(size_t)row * 16 + lane] = (lane == 0) ? ss : 0.f;
	v_add_f32_e32 v160, v160, v164
	v_add_f32_e32 v161, v161, v165
	v_add_f32_e32 v162, v162, v166
	v_add_f32_e32 v163, v163, v167
	ds_bpermute_b32 v164, v131, v160
	ds_bpermute_b32 v165, v131, v161
	ds_bpermute_b32 v166, v131, v162
	ds_bpermute_b32 v167, v131, v163
	s_waitcnt lgkmcnt(0)
	v_add_f32_e32 v160, v160, v164
	v_add_f32_e32 v161, v161, v165
	v_add_f32_e32 v162, v162, v166
	v_add_f32_e32 v163, v163, v167
	ds_bpermute_b32 v164, v132, v160
	ds_bpermute_b32 v165, v132, v161
	ds_bpermute_b32 v166, v132, v162
	ds_bpermute_b32 v167, v132, v163
	s_waitcnt lgkmcnt(0)
	v_add_f32_e32 v160, v160, v164
	v_add_f32_e32 v161, v161, v165
	v_add_f32_e32 v162, v162, v166
	v_add_f32_e32 v163, v163, v167
	ds_bpermute_b32 v164, v133, v160
	ds_bpermute_b32 v165, v133, v161
	ds_bpermute_b32 v166, v133, v162
	ds_bpermute_b32 v167, v133, v163
	s_waitcnt lgkmcnt(0)
	v_add_f32_e32 v160, v160, v164
	v_add_f32_e32 v161, v161, v165
	v_add_f32_e32 v162, v162, v166
	v_add_f32_e32 v163, v163, v167
	ds_bpermute_b32 v164, v134, v160
	ds_bpermute_b32 v165, v134, v161
	ds_bpermute_b32 v166, v134, v162
	ds_bpermute_b32 v167, v134, v163
	s_waitcnt lgkmcnt(0)
	v_add_f32_e32 v160, v160, v164
	v_add_f32_e32 v161, v161, v165
	v_add_f32_e32 v162, v162, v166
	v_add_f32_e32 v163, v163, v167
	ds_bpermute_b32 v164, v135, v160
	ds_bpermute_b32 v165, v135, v161
	ds_bpermute_b32 v166, v135, v162
	ds_bpermute_b32 v167, v135, v163
	s_waitcnt lgkmcnt(0)
	v_add_f32_e32 v160, v160, v164
	v_add_f32_e32 v161, v161, v165
	v_add_f32_e32 v162, v162, v166
	v_add_f32_e32 v163, v163, v167
	v_cndmask_b32_e64 v164, 0, v160, s[12:13]
	v_cndmask_b32_e64 v165, 0, v161, s[12:13]
	v_cndmask_b32_e64 v166, 0, v162, s[12:13]
	v_cndmask_b32_e64 v167, 0, v163, s[12:13]
	s_mov_b64 exec, 0xffff
	global_store_dword v186, v164, s[6:7]
	global_store_dword v187, v165, s[6:7]
	global_store_dword v188, v166, s[6:7]
	global_store_dword v189, v167, s[6:7]
	s_mov_b64 exec, -1
	s_add_i32 s6, s3, 0x7000
	s_lshl_b32 s6, s6, 12
	s_add_u32 s4, s18, s6
	s_addc_u32 s5, s19, 0
	global_load_dwordx4 v[66:69], v140, s[4:5] nt
	global_load_dwordx4 v[70:73], v140, s[4:5] offset:1024 nt
	global_load_dwordx4 v[74:77], v140, s[4:5] offset:2048 nt
	global_load_dwordx4 v[78:81], v140, s[4:5] offset:3072 nt
	global_load_dwordx4 v[82:85], v141, s[4:5] nt
	global_load_dwordx4 v[86:89], v141, s[4:5] offset:1024 nt
	global_load_dwordx4 v[90:93], v141, s[4:5] offset:2048 nt
	global_load_dwordx4 v[94:97], v141, s[4:5] offset:3072 nt
	global_load_dwordx4 v[98:101], v142, s[4:5] nt
	global_load_dwordx4 v[102:105], v142, s[4:5] offset:1024 nt
	global_load_dwordx4 v[106:109], v142, s[4:5] offset:2048 nt
	global_load_dwordx4 v[110:113], v142, s[4:5] offset:3072 nt
	global_load_dwordx4 v[114:117], v143, s[4:5] nt
	global_load_dwordx4 v[118:121], v143, s[4:5] offset:1024 nt
	global_load_dwordx4 v[122:125], v143, s[4:5] offset:2048 nt
	global_load_dwordx4 v[126:129], v143, s[4:5] offset:3072 nt
	s_waitcnt vmcnt(36)
	s_add_i32 s6, s3, 0xa000
	s_lshl_b32 s7, s6, 11
	s_add_u32 s10, s40, s7
	s_addc_u32 s11, s41, 0
	s_lshl_b32 s7, s6, 6
	s_add_u32 s6, s40, s7
	s_addc_u32 s7, s41, 0
	s_add_u32 s6, s6, 0x1f800000
	s_addc_u32 s7, s7, 0
	v_mul_f32_e32 v150, v3, v3
	v_mul_f32_e32 v151, v5, v5
	v_fmac_f32_e32 v150, v2, v2
	v_fmac_f32_e32 v151, v4, v4
	v_add_f32_e32 v160, v150, v151
	v_cvt_pk_f16_f32 v170, v2, v3
	v_cvt_pk_f16_f32 v171, v4, v5
	v_mul_f32_e32 v150, v7, v7
	v_mul_f32_e32 v151, v9, v9
	v_fmac_f32_e32 v150, v6, v6
	v_fmac_f32_e32 v151, v8, v8
	v_add_f32_e32 v152, v150, v151
	v_add_f32_e32 v160, v160, v152
	v_cvt_pk_f16_f32 v172, v6, v7
	v_cvt_pk_f16_f32 v173, v8, v9
	v_mul_f32_e32 v150, v11, v11
	v_mul_f32_e32 v151, v13, v13
	v_fmac_f32_e32 v150, v10, v10
	v_fmac_f32_e32 v151, v12, v12
	v_add_f32_e32 v152, v150, v151
	v_add_f32_e32 v160, v160, v152
	v_cvt_pk_f16_f32 v174, v10, v11
	v_cvt_pk_f16_f32 v175, v12, v13
	v_mul_f32_e32 v150, v15, v15
	v_mul_f32_e32 v151, v17, v17
	v_fmac_f32_e32 v150, v14, v14
	v_fmac_f32_e32 v151, v16, v16
	v_add_f32_e32 v152, v150, v151
	v_add_f32_e32 v160, v160, v152
	v_cvt_pk_f16_f32 v176, v14, v15
	v_cvt_pk_f16_f32 v177, v16, v17
	global_store_dwordx2 v144, v[170:171], s[10:11] nt
	global_store_dwordx2 v144, v[172:173], s[10:11] offset:512 nt
	global_store_dwordx2 v144, v[174:175], s[10:11] offset:1024 nt
	global_store_dwordx2 v144, v[176:177], s[10:11] offset:1536 nt
	v_mul_f32_e32 v150, v19, v19
	v_mul_f32_e32 v151, v21, v21
	v_fmac_f32_e32 v150, v18, v18
	v_fmac_f32_e32 v151, v20, v20
	v_add_f32_e32 v161, v150, v151
	v_cvt_pk_f16_f32 v178, v18, v19
	v_cvt_pk_f16_f32 v179, v20, v21
	v_mul_f32_e32 v150, v23, v23
	v_mul_f32_e32 v151, v25, v25
	v_fmac_f32_e32 v150, v22, v22
	v_fmac_f32_e32 v151, v24, v24
	v_add_f32_e32 v152, v150, v151
	v_add_f32_e32 v161, v161, v152
	v_cvt_pk_f16_f32 v180, v22, v23
	v_cvt_pk_f16_f32 v181, v24, v25
	v_mul_f32_e32 v150, v27, v27
	v_mul_f32_e32 v151, v29, v29
	v_fmac_f32_e32 v150, v26, v26
	v_fmac_f32_e32 v151, v28, v28
	v_add_f32_e32 v152, v150, v151
	v_add_f32_e32 v161, v161, v152
	v_cvt_pk_f16_f32 v182, v26, v27
	v_cvt_pk_f16_f32 v183, v28, v29
	v_mul_f32_e32 v150, v31, v31
	v_mul_f32_e32 v151, v33, v33
	v_fmac_f32_e32 v150, v30, v30
	v_fmac_f32_e32 v151, v32, v32
	v_add_f32_e32 v152, v150, v151
	v_add_f32_e32 v161, v161, v152
	v_cvt_pk_f16_f32 v184, v30, v31
	v_cvt_pk_f16_f32 v185, v32, v33
	global_store_dwordx2 v145, v[178:179], s[10:11] nt
	global_store_dwordx2 v145, v[180:181], s[10:11] offset:512 nt
	global_store_dwordx2 v145, v[182:183], s[10:11] offset:1024 nt
	global_store_dwordx2 v145, v[184:185], s[10:11] offset:1536 nt
	v_mul_f32_e32 v150, v35, v35
	v_mul_f32_e32 v151, v37, v37
; __device__ void p0_xconv(const Args& a) {
;     ...
;         for (int r = 0; r < 4; ++r) {
;             const int row = row0 + r * nwv;
;             if (row < MROWS) {
;                 float ss = 0.f;
; #pragma unroll
;                 for (int i = 0; i < 4; ++i) {
;                     const f32x4 x = v[r][i];
;                     ss += (x[0] * x[0] + x[1] * x[1]) + (x[2] * x[2] + x[3] * x[3]);
;                     f16x4 h; h[0] = (f16)x[0]; h[1] = (f16)x[1]; h[2] = (f16)x[2]; h[3] = (f16)x[3];
;                     *(f16x4*)(XH + (size_t)row * DM + i * 256 + lane * 4) = h;
;                 }
; #pragma unroll
;                 for (int o = 1; o < 64; o <<= 1) ss += __shfl_xor(ss, o);
;                 if (lane < 16) SS[(size_t)row * 16 + lane] = (lane == 0) ? ss : 0.f;
	v_fmac_f32_e32 v150, v34, v34
	v_fmac_f32_e32 v151, v36, v36
	v_add_f32_e32 v162, v150, v151
	v_cvt_pk_f16_f32 v170, v34, v35
	v_cvt_pk_f16_f32 v171, v36, v37
	v_mul_f32_e32 v150, v39, v39
	v_mul_f32_e32 v151, v41, v41
	v_fmac_f32_e32 v150, v38, v38
	v_fmac_f32_e32 v151, v40, v40
	v_add_f32_e32 v152, v150, v151
	v_add_f32_e32 v162, v162, v152
	v_cvt_pk_f16_f32 v172, v38, v39
	v_cvt_pk_f16_f32 v173, v40, v41
	v_mul_f32_e32 v150, v43, v43
	v_mul_f32_e32 v151, v45, v45
	v_fmac_f32_e32 v150, v42, v42
	v_fmac_f32_e32 v151, v44, v44
	v_add_f32_e32 v152, v150, v151
	v_add_f32_e32 v162, v162, v152
	v_cvt_pk_f16_f32 v174, v42, v43
	v_cvt_pk_f16_f32 v175, v44, v45
	v_mul_f32_e32 v150, v47, v47
	v_mul_f32_e32 v151, v49, v49
	v_fmac_f32_e32 v150, v46, v46
	v_fmac_f32_e32 v151, v48, v48
	v_add_f32_e32 v152, v150, v151
	v_add_f32_e32 v162, v162, v152
	v_cvt_pk_f16_f32 v176, v46, v47
	v_cvt_pk_f16_f32 v177, v48, v49
	global_store_dwordx2 v146, v[170:171], s[10:11] nt
	global_store_dwordx2 v146, v[172:173], s[10:11] offset:512 nt
	global_store_dwordx2 v146, v[174:175], s[10:11] offset:1024 nt
	global_store_dwordx2 v146, v[176:177], s[10:11] offset:1536 nt
	v_mul_f32_e32 v150, v51, v51
	v_mul_f32_e32 v151, v53, v53
	v_fmac_f32_e32 v150, v50, v50
	v_fmac_f32_e32 v151, v52, v52
	v_add_f32_e32 v163, v150, v151
	v_cvt_pk_f16_f32 v178, v50, v51
	v_cvt_pk_f16_f32 v179, v52, v53
	v_mul_f32_e32 v150, v55, v55
	v_mul_f32_e32 v151, v57, v57
	v_fmac_f32_e32 v150, v54, v54
	v_fmac_f32_e32 v151, v56, v56
	v_add_f32_e32 v152, v150, v151
	v_add_f32_e32 v163, v163, v152
	v_cvt_pk_f16_f32 v180, v54, v55
	v_cvt_pk_f16_f32 v181, v56, v57
	v_mul_f32_e32 v150, v59, v59
	v_mul_f32_e32 v151, v61, v61
	v_fmac_f32_e32 v150, v58, v58
	v_fmac_f32_e32 v151, v60, v60
	v_add_f32_e32 v152, v150, v151
	v_add_f32_e32 v163, v163, v152
	v_cvt_pk_f16_f32 v182, v58, v59
	v_cvt_pk_f16_f32 v183, v60, v61
	v_mul_f32_e32 v150, v63, v63
	v_mul_f32_e32 v151, v65, v65
	v_fmac_f32_e32 v150, v62, v62
	v_fmac_f32_e32 v151, v64, v64
	v_add_f32_e32 v152, v150, v151
	v_add_f32_e32 v163, v163, v152
	v_cvt_pk_f16_f32 v184, v62, v63
	v_cvt_pk_f16_f32 v185, v64, v65
	global_store_dwordx2 v147, v[178:179], s[10:11] nt
	global_store_dwordx2 v147, v[180:181], s[10:11] offset:512 nt
	global_store_dwordx2 v147, v[182:183], s[10:11] offset:1024 nt
	global_store_dwordx2 v147, v[184:185], s[10:11] offset:1536 nt
	ds_bpermute_b32 v164, v130, v160
	ds_bpermute_b32 v165, v130, v161
	ds_bpermute_b32 v166, v130, v162
	ds_bpermute_b32 v167, v130, v163
	s_waitcnt lgkmcnt(0)
	v_add_f32_e32 v160, v160, v164
	v_add_f32_e32 v161, v161, v165
	v_add_f32_e32 v162, v162, v166
	v_add_f32_e32 v163, v163, v167
	ds_bpermute_b32 v164, v131, v160
	ds_bpermute_b32 v165, v131, v161
	ds_bpermute_b32 v166, v131, v162
	ds_bpermute_b32 v167, v131, v163
	s_waitcnt lgkmcnt(0)
	v_add_f32_e32 v160, v160, v164
	v_add_f32_e32 v161, v161, v165
	v_add_f32_e32 v162, v162, v166
	v_add_f32_e32 v163, v163, v167
	ds_bpermute_b32 v164, v132, v160
	ds_bpermute_b32 v165, v132, v161
	ds_bpermute_b32 v166, v132, v162
	ds_bpermute_b32 v167, v132, v163
	s_waitcnt lgkmcnt(0)
	v_add_f32_e32 v160, v160, v164
	v_add_f32_e32 v161, v161, v165
	v_add_f32_e32 v162, v162, v166
	v_add_f32_e32 v163, v163, v167
	ds_bpermute_b32 v164, v133, v160
	ds_bpermute_b32 v165, v133, v161
	ds_bpermute_b32 v166, v133, v162
	ds_bpermute_b32 v167, v133, v163
	s_waitcnt lgkmcnt(0)
	v_add_f32_e32 v160, v160, v164
	v_add_f32_e32 v161, v161, v165
	v_add_f32_e32 v162, v162, v166
	v_add_f32_e32 v163, v163, v167
	ds_bpermute_b32 v164, v134, v160
	ds_bpermute_b32 v165, v134, v161
	ds_bpermute_b32 v166, v134, v162
	ds_bpermute_b32 v167, v134, v163
	s_waitcnt lgkmcnt(0)
	v_add_f32_e32 v160, v160, v164
	v_add_f32_e32 v161, v161, v165
	v_add_f32_e32 v162, v162, v166
	v_add_f32_e32 v163, v163, v167
	ds_bpermute_b32 v164, v135, v160
	ds_bpermute_b32 v165, v135, v161
	ds_bpermute_b32 v166, v135, v162
	ds_bpermute_b32 v167, v135, v163
	s_waitcnt lgkmcnt(0)
	v_add_f32_e32 v160, v160, v164
	v_add_f32_e32 v161, v161, v165
	v_add_f32_e32 v162, v162, v166
	v_add_f32_e32 v163, v163, v167
	v_cndmask_b32_e64 v164, 0, v160, s[12:13]
	v_cndmask_b32_e64 v165, 0, v161, s[12:13]
	v_cndmask_b32_e64 v166, 0, v162, s[12:13]
	v_cndmask_b32_e64 v167, 0, v163, s[12:13]
	s_mov_b64 exec, 0xffff
	global_store_dword v186, v164, s[6:7]
	global_store_dword v187, v165, s[6:7]
	global_store_dword v188, v166, s[6:7]
	global_store_dword v189, v167, s[6:7]
	s_mov_b64 exec, -1
	s_waitcnt vmcnt(20)
; __device__ void p0_xconv(const Args& a) {
;     ...
;         for (int r = 0; r < 4; ++r) {
;             const int row = row0 + r * nwv;
;             if (row < MROWS) {
;                 float ss = 0.f;
; #pragma unroll
;                 for (int i = 0; i < 4; ++i) {
;                     const f32x4 x = v[r][i];
;                     ss += (x[0] * x[0] + x[1] * x[1]) + (x[2] * x[2] + x[3] * x[3]);
;                     f16x4 h; h[0] = (f16)x[0]; h[1] = (f16)x[1]; h[2] = (f16)x[2]; h[3] = (f16)x[3];
;                     *(f16x4*)(XH + (size_t)row * DM + i * 256 + lane * 4) = h;
;                 }
; #pragma unroll
;                 for (int o = 1; o < 64; o <<= 1) ss += __shfl_xor(ss, o);
;                 if (lane < 16) SS[(size_t)row * 16 + lane] = (lane == 0) ? ss : 0.f;
	s_add_i32 s6, s3, 0xb000
	s_lshl_b32 s7, s6, 11
	s_add_u32 s10, s40, s7
	s_addc_u32 s11, s41, 0
	s_lshl_b32 s7, s6, 6
	s_add_u32 s6, s40, s7
	s_addc_u32 s7, s41, 0
	s_add_u32 s6, s6, 0x1f800000
	s_addc_u32 s7, s7, 0
	v_mul_f32_e32 v150, v67, v67
	v_mul_f32_e32 v151, v69, v69
	v_fmac_f32_e32 v150, v66, v66
	v_fmac_f32_e32 v151, v68, v68
	v_add_f32_e32 v160, v150, v151
	v_cvt_pk_f16_f32 v170, v66, v67
	v_cvt_pk_f16_f32 v171, v68, v69
	v_mul_f32_e32 v150, v71, v71
	v_mul_f32_e32 v151, v73, v73
	v_fmac_f32_e32 v150, v70, v70
	v_fmac_f32_e32 v151, v72, v72
	v_add_f32_e32 v152, v150, v151
	v_add_f32_e32 v160, v160, v152
	v_cvt_pk_f16_f32 v172, v70, v71
	v_cvt_pk_f16_f32 v173, v72, v73
	v_mul_f32_e32 v150, v75, v75
	v_mul_f32_e32 v151, v77, v77
	v_fmac_f32_e32 v150, v74, v74
	v_fmac_f32_e32 v151, v76, v76
	v_add_f32_e32 v152, v150, v151
	v_add_f32_e32 v160, v160, v152
	v_cvt_pk_f16_f32 v174, v74, v75
	v_cvt_pk_f16_f32 v175, v76, v77
	v_mul_f32_e32 v150, v79, v79
	v_mul_f32_e32 v151, v81, v81
	v_fmac_f32_e32 v150, v78, v78
	v_fmac_f32_e32 v151, v80, v80
	v_add_f32_e32 v152, v150, v151
	v_add_f32_e32 v160, v160, v152
	v_cvt_pk_f16_f32 v176, v78, v79
	v_cvt_pk_f16_f32 v177, v80, v81
	global_store_dwordx2 v144, v[170:171], s[10:11] nt
	global_store_dwordx2 v144, v[172:173], s[10:11] offset:512 nt
	global_store_dwordx2 v144, v[174:175], s[10:11] offset:1024 nt
	global_store_dwordx2 v144, v[176:177], s[10:11] offset:1536 nt
	v_mul_f32_e32 v150, v83, v83
	v_mul_f32_e32 v151, v85, v85
	v_fmac_f32_e32 v150, v82, v82
	v_fmac_f32_e32 v151, v84, v84
	v_add_f32_e32 v161, v150, v151
	v_cvt_pk_f16_f32 v178, v82, v83
	v_cvt_pk_f16_f32 v179, v84, v85
	v_mul_f32_e32 v150, v87, v87
	v_mul_f32_e32 v151, v89, v89
	v_fmac_f32_e32 v150, v86, v86
	v_fmac_f32_e32 v151, v88, v88
	v_add_f32_e32 v152, v150, v151
	v_add_f32_e32 v161, v161, v152
	v_cvt_pk_f16_f32 v180, v86, v87
	v_cvt_pk_f16_f32 v181, v88, v89
	v_mul_f32_e32 v150, v91, v91
	v_mul_f32_e32 v151, v93, v93
	v_fmac_f32_e32 v150, v90, v90
	v_fmac_f32_e32 v151, v92, v92
	v_add_f32_e32 v152, v150, v151
	v_add_f32_e32 v161, v161, v152
	v_cvt_pk_f16_f32 v182, v90, v91
	v_cvt_pk_f16_f32 v183, v92, v93
	v_mul_f32_e32 v150, v95, v95
	v_mul_f32_e32 v151, v97, v97
	v_fmac_f32_e32 v150, v94, v94
	v_fmac_f32_e32 v151, v96, v96
	v_add_f32_e32 v152, v150, v151
	v_add_f32_e32 v161, v161, v152
	v_cvt_pk_f16_f32 v184, v94, v95
	v_cvt_pk_f16_f32 v185, v96, v97
	global_store_dwordx2 v145, v[178:179], s[10:11] nt
	global_store_dwordx2 v145, v[180:181], s[10:11] offset:512 nt
	global_store_dwordx2 v145, v[182:183], s[10:11] offset:1024 nt
	global_store_dwordx2 v145, v[184:185], s[10:11] offset:1536 nt
	v_mul_f32_e32 v150, v99, v99
	v_mul_f32_e32 v151, v101, v101
	v_fmac_f32_e32 v150, v98, v98
	v_fmac_f32_e32 v151, v100, v100
	v_add_f32_e32 v162, v150, v151
	v_cvt_pk_f16_f32 v170, v98, v99
	v_cvt_pk_f16_f32 v171, v100, v101
	v_mul_f32_e32 v150, v103, v103
	v_mul_f32_e32 v151, v105, v105
	v_fmac_f32_e32 v150, v102, v102
	v_fmac_f32_e32 v151, v104, v104
	v_add_f32_e32 v152, v150, v151
	v_add_f32_e32 v162, v162, v152
	v_cvt_pk_f16_f32 v172, v102, v103
	v_cvt_pk_f16_f32 v173, v104, v105
	v_mul_f32_e32 v150, v107, v107
	v_mul_f32_e32 v151, v109, v109
	v_fmac_f32_e32 v150, v106, v106
	v_fmac_f32_e32 v151, v108, v108
	v_add_f32_e32 v152, v150, v151
	v_add_f32_e32 v162, v162, v152
	v_cvt_pk_f16_f32 v174, v106, v107
	v_cvt_pk_f16_f32 v175, v108, v109
	v_mul_f32_e32 v150, v111, v111
	v_mul_f32_e32 v151, v113, v113
	v_fmac_f32_e32 v150, v110, v110
	v_fmac_f32_e32 v151, v112, v112
	v_add_f32_e32 v152, v150, v151
	v_add_f32_e32 v162, v162, v152
	v_cvt_pk_f16_f32 v176, v110, v111
	v_cvt_pk_f16_f32 v177, v112, v113
	global_store_dwordx2 v146, v[170:171], s[10:11] nt
	global_store_dwordx2 v146, v[172:173], s[10:11] offset:512 nt
	global_store_dwordx2 v146, v[174:175], s[10:11] offset:1024 nt
	global_store_dwordx2 v146, v[176:177], s[10:11] offset:1536 nt
	v_mul_f32_e32 v150, v115, v115
	v_mul_f32_e32 v151, v117, v117
	v_fmac_f32_e32 v150, v114, v114
	v_fmac_f32_e32 v151, v116, v116
	v_add_f32_e32 v163, v150, v151
	v_cvt_pk_f16_f32 v178, v114, v115
	v_cvt_pk_f16_f32 v179, v116, v117
	v_mul_f32_e32 v150, v119, v119
	v_mul_f32_e32 v151, v121, v121
	v_fmac_f32_e32 v150, v118, v118
	v_fmac_f32_e32 v151, v120, v120
	v_add_f32_e32 v152, v150, v151
	v_add_f32_e32 v163, v163, v152
	v_cvt_pk_f16_f32 v180, v118, v119
	v_cvt_pk_f16_f32 v181, v120, v121
	v_mul_f32_e32 v150, v123, v123
	v_mul_f32_e32 v151, v125, v125
	v_fmac_f32_e32 v150, v122, v122
	v_fmac_f32_e32 v151, v124, v124
	v_add_f32_e32 v152, v150, v151
	v_add_f32_e32 v163, v163, v152
	v_cvt_pk_f16_f32 v182, v122, v123
	v_cvt_pk_f16_f32 v183, v124, v125
	v_mul_f32_e32 v150, v127, v127
	v_mul_f32_e32 v151, v129, v129
	v_fmac_f32_e32 v150, v126, v126
	v_fmac_f32_e32 v151, v128, v128
	v_add_f32_e32 v152, v150, v151
	v_add_f32_e32 v163, v163, v152
	v_cvt_pk_f16_f32 v184, v126, v127
	v_cvt_pk_f16_f32 v185, v128, v129
	global_store_dwordx2 v147, v[178:179], s[10:11] nt
	global_store_dwordx2 v147, v[180:181], s[10:11] offset:512 nt
	global_store_dwordx2 v147, v[182:183], s[10:11] offset:1024 nt
	global_store_dwordx2 v147, v[184:185], s[10:11] offset:1536 nt
	ds_bpermute_b32 v164, v130, v160
	ds_bpermute_b32 v165, v130, v161
	ds_bpermute_b32 v166, v130, v162
	ds_bpermute_b32 v167, v130, v163
	s_waitcnt lgkmcnt(0)
; __device__ void p0_xconv(const Args& a) {
;     ...
;                 for (int o = 1; o < 64; o <<= 1) ss += __shfl_xor(ss, o);
;                 if (lane < 16) SS[(size_t)row * 16 + lane] = (lane == 0) ? ss : 0.f;
	v_add_f32_e32 v160, v160, v164
	v_add_f32_e32 v161, v161, v165
	v_add_f32_e32 v162, v162, v166
	v_add_f32_e32 v163, v163, v167
	ds_bpermute_b32 v164, v131, v160
	ds_bpermute_b32 v165, v131, v161
	ds_bpermute_b32 v166, v131, v162
	ds_bpermute_b32 v167, v131, v163
	s_waitcnt lgkmcnt(0)
	v_add_f32_e32 v160, v160, v164
	v_add_f32_e32 v161, v161, v165
	v_add_f32_e32 v162, v162, v166
	v_add_f32_e32 v163, v163, v167
	ds_bpermute_b32 v164, v132, v160
	ds_bpermute_b32 v165, v132, v161
	ds_bpermute_b32 v166, v132, v162
	ds_bpermute_b32 v167, v132, v163
	s_waitcnt lgkmcnt(0)
	v_add_f32_e32 v160, v160, v164
	v_add_f32_e32 v161, v161, v165
	v_add_f32_e32 v162, v162, v166
	v_add_f32_e32 v163, v163, v167
	ds_bpermute_b32 v164, v133, v160
	ds_bpermute_b32 v165, v133, v161
	ds_bpermute_b32 v166, v133, v162
	ds_bpermute_b32 v167, v133, v163
	s_waitcnt lgkmcnt(0)
	v_add_f32_e32 v160, v160, v164
	v_add_f32_e32 v161, v161, v165
	v_add_f32_e32 v162, v162, v166
	v_add_f32_e32 v163, v163, v167
	ds_bpermute_b32 v164, v134, v160
	ds_bpermute_b32 v165, v134, v161
	ds_bpermute_b32 v166, v134, v162
	ds_bpermute_b32 v167, v134, v163
	s_waitcnt lgkmcnt(0)
	v_add_f32_e32 v160, v160, v164
	v_add_f32_e32 v161, v161, v165
	v_add_f32_e32 v162, v162, v166
	v_add_f32_e32 v163, v163, v167
	ds_bpermute_b32 v164, v135, v160
	ds_bpermute_b32 v165, v135, v161
	ds_bpermute_b32 v166, v135, v162
	ds_bpermute_b32 v167, v135, v163
	s_waitcnt lgkmcnt(0)
	v_add_f32_e32 v160, v160, v164
	v_add_f32_e32 v161, v161, v165
	v_add_f32_e32 v162, v162, v166
	v_add_f32_e32 v163, v163, v167
	v_cndmask_b32_e64 v164, 0, v160, s[12:13]
	v_cndmask_b32_e64 v165, 0, v161, s[12:13]
	v_cndmask_b32_e64 v166, 0, v162, s[12:13]
	v_cndmask_b32_e64 v167, 0, v163, s[12:13]
	s_mov_b64 exec, 0xffff
	global_store_dword v186, v164, s[6:7]
	global_store_dword v187, v165, s[6:7]
	global_store_dword v188, v166, s[6:7]
	global_store_dword v189, v167, s[6:7]
	s_mov_b64 exec, -1
	s_barrier
	s_branch .LBB0_112
